# v7 + half of the CUs start each GEMM phase a few us late (desynchronise init/epilogue memory bursts)
# baseline (speedup 1.0000x reference)
; __global__ void __launch_bounds__(512, 2) hymba_fwd(Args args) {
;     ...
;     if (IN(1)) for (int rep_ = 0; rep_ < REPS(1); ++rep_) {
;         pg8::ProbGrid P{XB, WinT, 2048, 2048, 32}; pg8::OrdGrid S; S.init(M, 4096, G, bx);
;         pg8::EpiZ E{ZA, Gb, SSQQ, SSQKV, SSQ1};
;         pg8::gemm_phase(lds + RING_OFF, P, S, E);
.LBB0_250:
	s_bitcmp1_b32 s96, 3
	s_cbranch_scc0 .Lstag_p1
	s_sleep 127
	s_sleep 127

; __global__ void __launch_bounds__(512, 2) hymba_fwd(Args args) {
;     ...
;     if (IN(5)) for (int rep_ = 0; rep_ < REPS(5); ++rep_) {
;         pg8::ProbGrid P{X1B, WupT, 2048, 2048, 32}; pg8::OrdGrid S; S.init(M, 2 * DFF, G, bx);
;         pg8::EpiUp E{A2, HALO, SSQ2, CWS, (PROBE_DRY && rep_ == 0) ? 1 : 0};
;         pg8::gemm_phase(lds + RING_OFF, P, S, E);
.LBB0_945:
	s_bitcmp1_b32 s96, 3
	s_cbranch_scc0 .Lstag_p5
	s_sleep 127

; __global__ void __launch_bounds__(512, 2) hymba_fwd(Args args) {
;     ...
;     if (IN(7)) {
;         pg8::ProbGrid P{A2, WdT, DFF, DFF, 88}; pg8::OrdPanel S{G, bx};
;         pg8::EpiDown E{X1B, out, fin_g, (unsigned*)SSQ3, (unsigned*)(ctl + CW_PANEL), (unsigned*)(ctl + CW_TMO)};
;         pg8::gemm_phase(lds + RING_OFF, P, S, E);
.LBB0_1150:
	s_bitcmp1_b32 s96, 3
	s_cbranch_scc0 .Lstag_p7
	s_sleep 127
	s_sleep 127
	s_sleep 127
